# speedup vs baseline: 1.0220x; 1.0220x over previous
; #define MFMA_FENCE() do { __builtin_amdgcn_sched_barrier(0); asm volatile("s_nop 15\n\ts_nop 15" ::: "memory"); __builtin_amdgcn_sched_barrier(0); } while (0)
; DEVI f32x16 mfma32(bf16x8 a, bf16x8 b, f32x16 c) { return __builtin_amdgcn_mfma_f32_32x32x16_bf16(a, b, c, 0, 0, 0); }
; template <bool SBK>
; __device__ __forceinline__ void attn_item(KP p, int layer, int b, int hh, int qt, char* smem, int tix) {
;     ...
;     if (kt * 64 <= qmax_w && !sb_done) {
;       f32x16 s[2];
;       __builtin_amdgcn_s_setprio(1);
; #pragma unroll
;       for (int kb2 = 0; kb2 < 2; ++kb2) {
; #pragma unroll
;         for (int r = 0; r < 16; ++r) s[kb2][r] = 0.f;
; #pragma unroll
;         for (int ks = 0; ks < 4; ++ks) {
;           bf16x8 a = *(const bf16x8*)(kb + (kb2 * 32 + l32) * KST + c * 64 + ks * 16 + hf * 8);
;           s[kb2] = mfma32(a, qf[ks], s[kb2]);
;         }
;       }
;       __builtin_amdgcn_s_setprio(0);
;       bf16x8 pf[2][2];
;       MFMA_FENCE();
;       if (!SBK) {
;         const bool need_mask = (kt * 64 + 63 > qmin_w) || (kt == 1);
;         float mx = -1e30f;
; #pragma unroll
;         for (int kb2 = 0; kb2 < 2; ++kb2)
; #pragma unroll
;           for (int r = 0; r < 16; ++r) {
;             float t = s[kb2][r] * sc2;
;             if (need_mask) {
;               int kp = kt * 64 + kb2 * 32 + 8 * (r >> 2) + 4 * hf + (r & 3);
;               if (kp < PADF || kp > qpos) t = -1e30f;
.LBB0_389:
	s_or_b64 exec, exec, s[6:7]
	s_sub_i32 s6, s14, 64
	v_cmp_le_i32_e32 vcc, s6, v141
	s_and_saveexec_b64 s[18:19], vcc
	s_cbranch_execz .LBB0_393
	s_bitcmp1_b32 s8, 0
	s_setprio 1
	s_cselect_b32 s7, 0x2200, 0
	s_lshl_b32 s15, s7, 1
	v_add3_u32 v161, v151, s15, v157
	ds_read_b128 v[66:69], v161
	ds_read_b128 v[70:73], v161 offset:32
	s_waitcnt lgkmcnt(1)
	v_mfma_f32_32x32x16_bf16 v[82:97], v[66:69], v[98:101], 0
	ds_read_b128 v[66:69], v161 offset:64
	ds_read_b128 v[162:165], v161 offset:8736
	s_waitcnt lgkmcnt(2)
	v_mfma_f32_32x32x16_bf16 v[82:97], v[70:73], v[102:105], v[82:97]
	s_waitcnt lgkmcnt(1)
	v_mfma_f32_32x32x16_bf16 v[82:97], v[66:69], v[106:109], v[82:97]
	ds_read_b128 v[66:69], v161 offset:96
	s_waitcnt lgkmcnt(0)
	v_mfma_f32_32x32x16_bf16 v[82:97], v[66:69], v[110:113], v[82:97]
	ds_read_b128 v[66:69], v161 offset:8704
	s_waitcnt lgkmcnt(0)
	v_mfma_f32_32x32x16_bf16 v[66:81], v[66:69], v[98:101], 0
	v_mfma_f32_32x32x16_bf16 v[66:81], v[162:165], v[102:105], v[66:81]
	ds_read_b128 v[162:165], v161 offset:8768
	s_waitcnt lgkmcnt(0)
	v_mfma_f32_32x32x16_bf16 v[66:81], v[162:165], v[106:109], v[66:81]
	ds_read_b128 v[162:165], v161 offset:8800
	s_waitcnt lgkmcnt(0)
	v_mfma_f32_32x32x16_bf16 v[66:81], v[162:165], v[110:113], v[66:81]
	s_setprio 0
	s_nop 15
	s_nop 15
	s_add_i32 s7, s14, -1
	v_add_u32_e32 v161, s14, v134
	v_subrev_u32_e32 v162, 64, v161
	s_cmpk_lt_u32 s6, 0x70
	v_cmp_gt_i32_e32 vcc, s7, v148
	s_cbranch_vccz .Ldiff_fast
	s_cselect_b64 s[8:9], -1, 0
	v_cmp_gt_i32_e64 s[6:7], v162, v133
	s_or_b64 s[6:7], s[8:9], s[6:7]
	v_mul_f32_e32 v82, 0x3e38aa3b, v82
	s_and_b64 s[6:7], vcc, s[6:7]
	v_cndmask_b32_e64 v82, v82, v182, s[6:7]
	v_cmp_ge_i32_e64 s[6:7], v162, v133
	s_or_b64 s[6:7], s[8:9], s[6:7]
	v_mul_f32_e32 v83, 0x3e38aa3b, v83
	s_and_b64 s[6:7], vcc, s[6:7]
	v_subrev_u32_e32 v163, 62, v161
	v_cndmask_b32_e64 v83, v83, v182, s[6:7]
	v_cmp_gt_i32_e64 s[6:7], v163, v133
	s_or_b64 s[6:7], s[8:9], s[6:7]
	v_mul_f32_e32 v84, 0x3e38aa3b, v84
	s_and_b64 s[6:7], vcc, s[6:7]
	v_subrev_u32_e32 v163, 61, v161
	v_cndmask_b32_e64 v84, v84, v182, s[6:7]
	v_cmp_gt_i32_e64 s[6:7], v163, v133
	s_or_b64 s[6:7], s[8:9], s[6:7]
	v_mul_f32_e32 v85, 0x3e38aa3b, v85
	s_and_b64 s[6:7], vcc, s[6:7]
	v_subrev_u32_e32 v163, 56, v161
	v_cndmask_b32_e64 v85, v85, v182, s[6:7]
	v_cmp_gt_i32_e64 s[6:7], v163, v133
	s_or_b64 s[6:7], s[8:9], s[6:7]
	v_mul_f32_e32 v86, 0x3e38aa3b, v86
	s_and_b64 s[6:7], vcc, s[6:7]
	v_subrev_u32_e32 v163, 55, v161
	v_cndmask_b32_e64 v86, v86, v182, s[6:7]
	v_cmp_gt_i32_e64 s[6:7], v163, v133
	s_or_b64 s[6:7], s[8:9], s[6:7]
	v_mul_f32_e32 v87, 0x3e38aa3b, v87
	s_and_b64 s[6:7], vcc, s[6:7]
	v_subrev_u32_e32 v163, 54, v161
	v_cndmask_b32_e64 v87, v87, v182, s[6:7]
	v_cmp_gt_i32_e64 s[6:7], v163, v133
	s_or_b64 s[6:7], s[8:9], s[6:7]
	v_mul_f32_e32 v88, 0x3e38aa3b, v88
	s_and_b64 s[6:7], vcc, s[6:7]
	v_subrev_u32_e32 v163, 53, v161
	v_cndmask_b32_e64 v88, v88, v182, s[6:7]
	v_cmp_gt_i32_e64 s[6:7], v163, v133
	s_or_b64 s[6:7], s[8:9], s[6:7]
	v_mul_f32_e32 v89, 0x3e38aa3b, v89
	s_and_b64 s[6:7], vcc, s[6:7]
	v_subrev_u32_e32 v163, 48, v161
	v_cndmask_b32_e64 v89, v89, v182, s[6:7]
	v_cmp_gt_u32_e64 s[6:7], s53, v163
	v_cmp_gt_i32_e64 s[8:9], v163, v133
	s_or_b64 s[6:7], s[6:7], s[8:9]
	v_mul_f32_e32 v90, 0x3e38aa3b, v90
	s_and_b64 s[6:7], vcc, s[6:7]
	v_subrev_u32_e32 v163, 47, v161
	v_cndmask_b32_e64 v90, v90, v182, s[6:7]
	v_cmp_gt_u32_e64 s[6:7], s53, v163
	v_cmp_gt_i32_e64 s[8:9], v163, v133
	s_or_b64 s[6:7], s[6:7], s[8:9]
	v_mul_f32_e32 v91, 0x3e38aa3b, v91
	s_and_b64 s[6:7], vcc, s[6:7]
	v_subrev_u32_e32 v163, 46, v161
	v_cndmask_b32_e64 v91, v91, v182, s[6:7]
	v_cmp_gt_u32_e64 s[6:7], s53, v163
	v_cmp_gt_i32_e64 s[8:9], v163, v133
	s_or_b64 s[6:7], s[6:7], s[8:9]
	v_mul_f32_e32 v92, 0x3e38aa3b, v92
	s_and_b64 s[6:7], vcc, s[6:7]
	v_subrev_u32_e32 v163, 45, v161
	v_cndmask_b32_e64 v92, v92, v182, s[6:7]
	v_cmp_gt_u32_e64 s[6:7], s53, v163
	v_cmp_gt_i32_e64 s[8:9], v163, v133
	s_or_b64 s[6:7], s[6:7], s[8:9]
	v_mul_f32_e32 v93, 0x3e38aa3b, v93
	s_and_b64 s[6:7], vcc, s[6:7]
	v_subrev_u32_e32 v163, 40, v161
	v_cndmask_b32_e64 v93, v93, v182, s[6:7]
	v_cmp_gt_u32_e64 s[6:7], s53, v163
	v_cmp_gt_i32_e64 s[8:9], v163, v133
	s_or_b64 s[6:7], s[6:7], s[8:9]
	v_mul_f32_e32 v94, 0x3e38aa3b, v94
	s_and_b64 s[6:7], vcc, s[6:7]
	v_subrev_u32_e32 v163, 39, v161
	v_cndmask_b32_e64 v94, v94, v182, s[6:7]
	v_cmp_gt_u32_e64 s[6:7], s53, v163
	v_cmp_gt_i32_e64 s[8:9], v163, v133
	s_or_b64 s[6:7], s[6:7], s[8:9]
	v_mul_f32_e32 v95, 0x3e38aa3b, v95
	s_and_b64 s[6:7], vcc, s[6:7]
	v_subrev_u32_e32 v163, 38, v161
	v_cndmask_b32_e64 v95, v95, v182, s[6:7]
	v_cmp_gt_u32_e64 s[6:7], s53, v163
	v_cmp_gt_i32_e64 s[8:9], v163, v133
	s_or_b64 s[6:7], s[6:7], s[8:9]
	v_mul_f32_e32 v96, 0x3e38aa3b, v96
	s_and_b64 s[6:7], vcc, s[6:7]
	v_subrev_u32_e32 v163, 37, v161
	v_cndmask_b32_e64 v96, v96, v182, s[6:7]
	v_cmp_gt_u32_e64 s[6:7], s53, v163
	v_cmp_gt_i32_e64 s[8:9], v163, v133
	s_or_b64 s[6:7], s[6:7], s[8:9]
	v_mul_f32_e32 v97, 0x3e38aa3b, v97
	s_and_b64 s[6:7], vcc, s[6:7]
	v_subrev_u32_e32 v163, 32, v161
	v_cndmask_b32_e64 v97, v97, v182, s[6:7]
	v_cmp_gt_u32_e64 s[6:7], s53, v163
	v_cmp_gt_i32_e64 s[8:9], v163, v133
	s_or_b64 s[6:7], s[6:7], s[8:9]
	v_mul_f32_e32 v66, 0x3e38aa3b, v66
	s_and_b64 s[6:7], vcc, s[6:7]
	v_subrev_u32_e32 v163, 31, v161
	v_cndmask_b32_e64 v66, v66, v182, s[6:7]
	v_cmp_gt_u32_e64 s[6:7], s53, v163
	v_cmp_gt_i32_e64 s[8:9], v163, v133
	s_or_b64 s[6:7], s[6:7], s[8:9]
	v_mul_f32_e32 v67, 0x3e38aa3b, v67
	s_and_b64 s[6:7], vcc, s[6:7]
	v_subrev_u32_e32 v163, 30, v161
	v_cndmask_b32_e64 v67, v67, v182, s[6:7]
; DEVI float max32x(float v) { float a, b; swap32(v, a, b); return fmaxf(a, b); }
; #define MFMA_FENCE() do { __builtin_amdgcn_sched_barrier(0); asm volatile("s_nop 15\n\ts_nop 15" ::: "memory"); __builtin_amdgcn_sched_barrier(0); } while (0)
; template <bool SBK>
; __device__ __forceinline__ void attn_item(KP p, int layer, int b, int hh, int qt, char* smem, int tix) {
;     ...
;         float mx = -1e30f;
; #pragma unroll
;         for (int kb2 = 0; kb2 < 2; ++kb2)
; #pragma unroll
;           for (int r = 0; r < 16; ++r) {
;             float t = s[kb2][r] * sc2;
;             if (need_mask) {
;               int kp = kt * 64 + kb2 * 32 + 8 * (r >> 2) + 4 * hf + (r & 3);
;               if (kp < PADF || kp > qpos) t = -1e30f;
;             }
;             s[kb2][r] = t;
;             mx = fmaxf(mx, t);
;           }
;         mx = max32x(mx);
;         if (__ballot(mx > m_run + 8.0f) != 0ull) {
;           const float m_new = fmaxf(m_run, mx);
;           const float alpha = __builtin_amdgcn_exp2f(m_run - m_new);
;           m_run = m_new;
;           l_run *= alpha;
;           MFMA_FENCE();
; #pragma unroll
;           for (int d = 0; d < NDV; ++d)
; #pragma unroll
;             for (int r = 0; r < 16; ++r) O[d][r] *= alpha;
;         }
	v_cmp_gt_u32_e64 s[6:7], s53, v163
	v_cmp_gt_i32_e64 s[8:9], v163, v133
	s_or_b64 s[6:7], s[6:7], s[8:9]
	v_mul_f32_e32 v68, 0x3e38aa3b, v68
	s_and_b64 s[6:7], vcc, s[6:7]
	v_subrev_u32_e32 v163, 29, v161
	v_cndmask_b32_e64 v68, v68, v182, s[6:7]
	v_cmp_gt_u32_e64 s[6:7], s53, v163
	v_cmp_gt_i32_e64 s[8:9], v163, v133
	s_or_b64 s[6:7], s[6:7], s[8:9]
	v_mul_f32_e32 v69, 0x3e38aa3b, v69
	s_and_b64 s[6:7], vcc, s[6:7]
	v_subrev_u32_e32 v163, 24, v161
	v_cndmask_b32_e64 v69, v69, v182, s[6:7]
	v_cmp_gt_u32_e64 s[6:7], s53, v163
	v_cmp_gt_i32_e64 s[8:9], v163, v133
	s_or_b64 s[6:7], s[6:7], s[8:9]
	v_mul_f32_e32 v70, 0x3e38aa3b, v70
	s_and_b64 s[6:7], vcc, s[6:7]
	v_subrev_u32_e32 v163, 23, v161
	v_cndmask_b32_e64 v70, v70, v182, s[6:7]
	v_cmp_gt_u32_e64 s[6:7], s53, v163
	v_cmp_gt_i32_e64 s[8:9], v163, v133
	s_or_b64 s[6:7], s[6:7], s[8:9]
	v_mul_f32_e32 v71, 0x3e38aa3b, v71
	s_and_b64 s[6:7], vcc, s[6:7]
	v_subrev_u32_e32 v163, 22, v161
	v_cndmask_b32_e64 v71, v71, v182, s[6:7]
	v_cmp_gt_u32_e64 s[6:7], s53, v163
	v_cmp_gt_i32_e64 s[8:9], v163, v133
	s_or_b64 s[6:7], s[6:7], s[8:9]
	v_mul_f32_e32 v72, 0x3e38aa3b, v72
	s_and_b64 s[6:7], vcc, s[6:7]
	v_subrev_u32_e32 v163, 21, v161
	v_cndmask_b32_e64 v72, v72, v182, s[6:7]
	v_cmp_gt_u32_e64 s[6:7], s53, v163
	v_cmp_gt_i32_e64 s[8:9], v163, v133
	s_or_b64 s[6:7], s[6:7], s[8:9]
	v_mul_f32_e32 v73, 0x3e38aa3b, v73
	s_and_b64 s[6:7], vcc, s[6:7]
	v_add_u32_e32 v163, -16, v161
	v_cndmask_b32_e64 v73, v73, v182, s[6:7]
	v_cmp_gt_u32_e64 s[6:7], s53, v163
	v_cmp_gt_i32_e64 s[8:9], v163, v133
	s_or_b64 s[6:7], s[6:7], s[8:9]
	v_mul_f32_e32 v74, 0x3e38aa3b, v74
	s_and_b64 s[6:7], vcc, s[6:7]
	v_add_u32_e32 v163, -15, v161
	v_cndmask_b32_e64 v74, v74, v182, s[6:7]
	v_cmp_gt_u32_e64 s[6:7], s53, v163
	v_cmp_gt_i32_e64 s[8:9], v163, v133
	s_or_b64 s[6:7], s[6:7], s[8:9]
	v_mul_f32_e32 v75, 0x3e38aa3b, v75
	s_and_b64 s[6:7], vcc, s[6:7]
	v_add_u32_e32 v163, -14, v161
	v_cndmask_b32_e64 v75, v75, v182, s[6:7]
	v_cmp_gt_u32_e64 s[6:7], s53, v163
	v_cmp_gt_i32_e64 s[8:9], v163, v133
	s_or_b64 s[6:7], s[6:7], s[8:9]
	v_mul_f32_e32 v76, 0x3e38aa3b, v76
	s_and_b64 s[6:7], vcc, s[6:7]
	v_add_u32_e32 v163, -13, v161
	v_cndmask_b32_e64 v76, v76, v182, s[6:7]
	v_cmp_gt_u32_e64 s[6:7], s53, v163
	v_cmp_gt_i32_e64 s[8:9], v163, v133
	v_max3_f32 v162, v82, s23, v83
	s_or_b64 s[6:7], s[6:7], s[8:9]
	v_max3_f32 v162, v162, v84, v85
	v_mul_f32_e32 v77, 0x3e38aa3b, v77
	s_and_b64 s[6:7], vcc, s[6:7]
	v_add_u32_e32 v163, -8, v161
	v_max3_f32 v162, v162, v86, v87
	v_cndmask_b32_e64 v77, v77, v182, s[6:7]
	v_cmp_gt_u32_e64 s[6:7], s53, v163
	v_cmp_gt_i32_e64 s[8:9], v163, v133
	v_max3_f32 v162, v162, v88, v89
	s_or_b64 s[6:7], s[6:7], s[8:9]
	v_max3_f32 v162, v162, v90, v91
	v_mul_f32_e32 v78, 0x3e38aa3b, v78
	s_and_b64 s[6:7], vcc, s[6:7]
	v_add_u32_e32 v163, -7, v161
	v_max3_f32 v162, v162, v92, v93
	v_cndmask_b32_e64 v78, v78, v182, s[6:7]
	v_cmp_gt_u32_e64 s[6:7], s53, v163
	v_cmp_gt_i32_e64 s[8:9], v163, v133
	v_max3_f32 v162, v162, v94, v95
	s_or_b64 s[6:7], s[6:7], s[8:9]
	v_max3_f32 v162, v162, v96, v97
	v_mul_f32_e32 v79, 0x3e38aa3b, v79
	s_and_b64 s[6:7], vcc, s[6:7]
	v_add_u32_e32 v163, -6, v161
	v_max3_f32 v162, v162, v66, v67
	v_cndmask_b32_e64 v79, v79, v182, s[6:7]
	v_cmp_gt_u32_e64 s[6:7], s53, v163
	v_cmp_gt_i32_e64 s[8:9], v163, v133
	v_max3_f32 v162, v162, v68, v69
	s_or_b64 s[6:7], s[6:7], s[8:9]
	v_max3_f32 v162, v162, v70, v71
	v_mul_f32_e32 v80, 0x3e38aa3b, v80
	s_and_b64 s[6:7], vcc, s[6:7]
	v_add_u32_e32 v161, -5, v161
	v_max3_f32 v162, v162, v72, v73
	v_cndmask_b32_e64 v80, v80, v182, s[6:7]
	v_cmp_gt_u32_e64 s[6:7], s53, v161
	v_cmp_gt_i32_e64 s[8:9], v161, v133
	v_max3_f32 v162, v162, v74, v75
	s_or_b64 s[6:7], s[6:7], s[8:9]
	v_max3_f32 v162, v162, v76, v77
	v_mul_f32_e32 v81, 0x3e38aa3b, v81
	s_and_b64 vcc, vcc, s[6:7]
	v_max3_f32 v162, v162, v78, v79
	v_cndmask_b32_e32 v81, v81, v182, vcc
	v_max3_f32 v161, v162, v80, v81
.Ldiff_join:
	v_mov_b32_e32 v162, v161
	s_nop 1
	v_permlane32_swap_b32_e32 v161, v162
	v_max_f32_e32 v162, v162, v162
	v_max_f32_e32 v161, v161, v161
	v_max_f32_e32 v161, v161, v162
	v_add_f32_e32 v162, 0x41000000, v155
	v_cmp_gt_f32_e32 vcc, v161, v162
	s_cbranch_vccz .LBB0_392
	v_max_f32_e32 v161, v161, v161
	v_max_f32_e32 v162, v155, v155
	v_max_f32_e32 v161, v162, v161
	v_sub_f32_e32 v155, v155, v161
	v_exp_f32_e32 v162, v155
	s_nop 15
	s_nop 15
	s_nop 0
	v_pk_mul_f32 v[64:65], v[64:65], v[162:163] op_sel_hi:[1,0]
	v_pk_mul_f32 v[62:63], v[62:63], v[162:163] op_sel_hi:[1,0]
	v_pk_mul_f32 v[60:61], v[60:61], v[162:163] op_sel_hi:[1,0]
	v_pk_mul_f32 v[58:59], v[58:59], v[162:163] op_sel_hi:[1,0]
	v_pk_mul_f32 v[56:57], v[56:57], v[162:163] op_sel_hi:[1,0]
	v_pk_mul_f32 v[54:55], v[54:55], v[162:163] op_sel_hi:[1,0]
	v_pk_mul_f32 v[52:53], v[52:53], v[162:163] op_sel_hi:[1,0]
	v_pk_mul_f32 v[50:51], v[50:51], v[162:163] op_sel_hi:[1,0]
	v_pk_mul_f32 v[48:49], v[48:49], v[162:163] op_sel_hi:[1,0]
	v_pk_mul_f32 v[46:47], v[46:47], v[162:163] op_sel_hi:[1,0]
	v_pk_mul_f32 v[44:45], v[44:45], v[162:163] op_sel_hi:[1,0]
	v_pk_mul_f32 v[42:43], v[42:43], v[162:163] op_sel_hi:[1,0]
	v_pk_mul_f32 v[40:41], v[40:41], v[162:163] op_sel_hi:[1,0]
	v_pk_mul_f32 v[38:39], v[38:39], v[162:163] op_sel_hi:[1,0]
	v_pk_mul_f32 v[36:37], v[36:37], v[162:163] op_sel_hi:[1,0]
	v_pk_mul_f32 v[34:35], v[34:35], v[162:163] op_sel_hi:[1,0]
	v_pk_mul_f32 v[32:33], v[32:33], v[162:163] op_sel_hi:[1,0]
	v_pk_mul_f32 v[30:31], v[30:31], v[162:163] op_sel_hi:[1,0]
	v_pk_mul_f32 v[28:29], v[28:29], v[162:163] op_sel_hi:[1,0]
	v_pk_mul_f32 v[26:27], v[26:27], v[162:163] op_sel_hi:[1,0]
	v_pk_mul_f32 v[24:25], v[24:25], v[162:163] op_sel_hi:[1,0]
	v_pk_mul_f32 v[22:23], v[22:23], v[162:163] op_sel_hi:[1,0]
	v_pk_mul_f32 v[20:21], v[20:21], v[162:163] op_sel_hi:[1,0]
	v_pk_mul_f32 v[18:19], v[18:19], v[162:163] op_sel_hi:[1,0]
	v_pk_mul_f32 v[16:17], v[16:17], v[162:163] op_sel_hi:[1,0]
	v_pk_mul_f32 v[14:15], v[14:15], v[162:163] op_sel_hi:[1,0]
	v_pk_mul_f32 v[12:13], v[12:13], v[162:163] op_sel_hi:[1,0]
	v_pk_mul_f32 v[10:11], v[10:11], v[162:163] op_sel_hi:[1,0]
	v_pk_mul_f32 v[8:9], v[8:9], v[162:163] op_sel_hi:[1,0]
	v_pk_mul_f32 v[6:7], v[6:7], v[162:163] op_sel_hi:[1,0]
	v_pk_mul_f32 v[4:5], v[4:5], v[162:163] op_sel_hi:[1,0]
	v_pk_mul_f32 v[2:3], v[2:3], v[162:163] op_sel_hi:[1,0]
	v_mul_f32_e32 v156, v156, v162
	v_mov_b32_e32 v155, v161

; DEVI float max32x(float v) { float a, b; swap32(v, a, b); return fmaxf(a, b); }
; template <bool SBK>
; __device__ __forceinline__ void attn_item(KP p, int layer, int b, int hh, int qt, char* smem, int tix) {
;     ...
;         const bool need_mask = (kt * 64 + 63 > qmin_w) || (kt == 1);
;         float mx = -1e30f;
; #pragma unroll
;         for (int kb2 = 0; kb2 < 2; ++kb2)
; #pragma unroll
;           for (int r = 0; r < 16; ++r) {
;             float t = s[kb2][r] * sc2;
;             if (need_mask) {
;               int kp = kt * 64 + kb2 * 32 + 8 * (r >> 2) + 4 * hf + (r & 3);
;               if (kp < PADF || kp > qpos) t = -1e30f;
;             }
;             s[kb2][r] = t;
;             mx = fmaxf(mx, t);
;           }
;         mx = max32x(mx);
.Ldiff_fast:
	v_mul_f32_e32 v82, 0x3e38aa3b, v82
	v_mul_f32_e32 v66, 0x3e38aa3b, v66
	v_mul_f32_e32 v83, 0x3e38aa3b, v83
	v_mul_f32_e32 v67, 0x3e38aa3b, v67
	v_mul_f32_e32 v84, 0x3e38aa3b, v84
	v_mul_f32_e32 v68, 0x3e38aa3b, v68
	v_mul_f32_e32 v85, 0x3e38aa3b, v85
	v_mul_f32_e32 v69, 0x3e38aa3b, v69
	v_mul_f32_e32 v86, 0x3e38aa3b, v86
	v_mul_f32_e32 v70, 0x3e38aa3b, v70
	v_mul_f32_e32 v87, 0x3e38aa3b, v87
	v_mul_f32_e32 v71, 0x3e38aa3b, v71
	v_mul_f32_e32 v88, 0x3e38aa3b, v88
	v_mul_f32_e32 v72, 0x3e38aa3b, v72
	v_mul_f32_e32 v89, 0x3e38aa3b, v89
	v_mul_f32_e32 v73, 0x3e38aa3b, v73
	v_mul_f32_e32 v90, 0x3e38aa3b, v90
	v_mul_f32_e32 v74, 0x3e38aa3b, v74
	v_mul_f32_e32 v91, 0x3e38aa3b, v91
	v_mul_f32_e32 v75, 0x3e38aa3b, v75
	v_mul_f32_e32 v92, 0x3e38aa3b, v92
	v_mul_f32_e32 v76, 0x3e38aa3b, v76
	v_mul_f32_e32 v93, 0x3e38aa3b, v93
	v_mul_f32_e32 v77, 0x3e38aa3b, v77
	v_mul_f32_e32 v94, 0x3e38aa3b, v94
	v_mul_f32_e32 v78, 0x3e38aa3b, v78
	v_mul_f32_e32 v95, 0x3e38aa3b, v95
	v_mul_f32_e32 v79, 0x3e38aa3b, v79
	v_mul_f32_e32 v96, 0x3e38aa3b, v96
	v_mul_f32_e32 v80, 0x3e38aa3b, v80
	v_mul_f32_e32 v97, 0x3e38aa3b, v97
	v_mul_f32_e32 v81, 0x3e38aa3b, v81
	v_max3_f32 v162, v82, s23, v83
	v_max3_f32 v163, v66, v67, v68
	v_max3_f32 v162, v162, v84, v85
	v_max3_f32 v163, v163, v69, v70
	v_max3_f32 v162, v162, v86, v87
	v_max3_f32 v163, v163, v71, v72
	v_max3_f32 v162, v162, v88, v89
	v_max3_f32 v163, v163, v73, v74
	v_max3_f32 v162, v162, v90, v91
	v_max3_f32 v163, v163, v75, v76
	v_max3_f32 v162, v162, v92, v93
	v_max3_f32 v163, v163, v77, v78
	v_max3_f32 v162, v162, v94, v95
	v_max3_f32 v163, v163, v79, v80
	v_max3_f32 v162, v162, v96, v97
	v_max3_f32 v161, v162, v163, v81
	s_branch .Ldiff_join
